# GEMM accumulator zeroing with 64-bit moves (64 instead of 128 VALU per tile)
# speedup vs baseline: 1.0390x; 1.0011x over previous
.LBB0_182:
	s_ashr_i32 s27, s26, 31
	s_lshl_b64 s[12:13], s[26:27], 19
	s_add_u32 s28, s16, s12
	s_addc_u32 s29, s17, s13
	s_and_b64 s[12:13], s[8:9], exec
	s_cselect_b32 s11, s29, s47
	s_cselect_b32 s27, s28, s46
	s_ashr_i32 s25, s24, 31
	s_lshl_b64 s[12:13], s[24:25], 19
	s_add_u32 s30, s0, s12
	s_addc_u32 s31, s1, s13
	s_and_b64 s[12:13], s[8:9], exec
	s_cselect_b32 s25, s31, s43
	s_cselect_b32 s35, s30, s42
	s_add_u32 s85, s42, 0x100
	s_addc_u32 s90, s43, 0
	s_add_u32 s42, s46, 0x40080
	v_mov_b64_e32 v[2:3], 0
	s_addc_u32 s43, s47, 0
	s_mov_b32 vcc_lo, -2
	v_mov_b64_e32 v[4:5], 0
	v_mov_b64_e32 v[6:7], 0
	v_mov_b64_e32 v[8:9], 0
	v_mov_b64_e32 v[18:19], 0
	v_mov_b64_e32 v[20:21], 0
	v_mov_b64_e32 v[22:23], 0
	v_mov_b64_e32 v[24:25], 0
	v_mov_b64_e32 v[34:35], 0
	v_mov_b64_e32 v[36:37], 0
	v_mov_b64_e32 v[38:39], 0
	v_mov_b64_e32 v[40:41], 0
	v_mov_b64_e32 v[62:63], 0
	v_mov_b64_e32 v[64:65], 0
	v_mov_b64_e32 v[66:67], 0
	v_mov_b64_e32 v[68:69], 0
	v_mov_b64_e32 v[10:11], 0
	v_mov_b64_e32 v[12:13], 0
	v_mov_b64_e32 v[14:15], 0
	v_mov_b64_e32 v[16:17], 0
	v_mov_b64_e32 v[26:27], 0
	v_mov_b64_e32 v[28:29], 0
	v_mov_b64_e32 v[30:31], 0
	v_mov_b64_e32 v[32:33], 0
	v_mov_b64_e32 v[46:47], 0
	v_mov_b64_e32 v[48:49], 0
	v_mov_b64_e32 v[50:51], 0
	v_mov_b64_e32 v[52:53], 0
	v_mov_b64_e32 v[74:75], 0
	v_mov_b64_e32 v[76:77], 0
	v_mov_b64_e32 v[78:79], 0
	v_mov_b64_e32 v[80:81], 0
	v_mov_b64_e32 v[82:83], 0
	v_mov_b64_e32 v[84:85], 0
	v_mov_b64_e32 v[86:87], 0
	v_mov_b64_e32 v[88:89], 0
	s_waitcnt vmcnt(0)
	v_mov_b64_e32 v[98:99], 0
	v_mov_b64_e32 v[100:101], 0
	v_mov_b64_e32 v[102:103], 0
	v_mov_b64_e32 v[104:105], 0
	v_mov_b64_e32 v[114:115], 0
	v_mov_b64_e32 v[116:117], 0
	v_mov_b64_e32 v[118:119], 0
	v_mov_b64_e32 v[120:121], 0
	v_mov_b64_e32 v[130:131], 0
	v_mov_b64_e32 v[132:133], 0
	v_mov_b64_e32 v[134:135], 0
	v_mov_b64_e32 v[136:137], 0
	v_mov_b64_e32 v[90:91], 0
	v_mov_b64_e32 v[92:93], 0
	v_mov_b64_e32 v[94:95], 0
	v_mov_b64_e32 v[96:97], 0
	v_mov_b64_e32 v[106:107], 0
	v_mov_b64_e32 v[108:109], 0
	v_mov_b64_e32 v[110:111], 0
	v_mov_b64_e32 v[112:113], 0
	v_mov_b64_e32 v[122:123], 0
	v_mov_b64_e32 v[124:125], 0
	v_mov_b64_e32 v[126:127], 0
	v_mov_b64_e32 v[128:129], 0
	v_mov_b64_e32 v[138:139], 0
	v_mov_b64_e32 v[140:141], 0
	v_mov_b64_e32 v[142:143], 0
	v_mov_b64_e32 v[144:145], 0

.LBB0_381:
	s_ashr_i32 s25, s24, 31
	s_lshl_b64 s[12:13], s[24:25], 19
	s_add_u32 s26, s16, s12
	s_addc_u32 s27, s17, s13
	s_and_b64 s[12:13], s[6:7], exec
	s_cselect_b32 s9, s27, s35
	s_cselect_b32 s11, s26, s34
	s_ashr_i32 s23, s22, 31
	s_lshl_b64 s[12:13], s[22:23], 19
	s_add_u32 s28, s0, s12
	s_addc_u32 s29, s1, s13
	s_and_b64 s[12:13], s[6:7], exec
	s_cselect_b32 s14, s29, s31
	s_cselect_b32 s23, s28, s30
	s_add_u32 s25, s30, 0x100
	s_addc_u32 s33, s31, 0
	s_add_u32 s30, s34, 0x40080
	s_waitcnt lgkmcnt(0)
	v_mov_b64_e32 v[2:3], 0
	s_addc_u32 s31, s35, 0
	s_mov_b32 s76, -2
	v_mov_b64_e32 v[4:5], 0
	v_mov_b64_e32 v[6:7], 0
	v_mov_b64_e32 v[8:9], 0
	v_mov_b64_e32 v[18:19], 0
	v_mov_b64_e32 v[20:21], 0
	v_mov_b64_e32 v[22:23], 0
	v_mov_b64_e32 v[24:25], 0
	v_mov_b64_e32 v[34:35], 0
	v_mov_b64_e32 v[36:37], 0
	v_mov_b64_e32 v[38:39], 0
	v_mov_b64_e32 v[40:41], 0
	v_mov_b64_e32 v[50:51], 0
	v_mov_b64_e32 v[52:53], 0
	v_mov_b64_e32 v[54:55], 0
	v_mov_b64_e32 v[56:57], 0
	v_mov_b64_e32 v[10:11], 0
	v_mov_b64_e32 v[12:13], 0
	v_mov_b64_e32 v[14:15], 0
	v_mov_b64_e32 v[16:17], 0
	v_mov_b64_e32 v[26:27], 0
	v_mov_b64_e32 v[28:29], 0
	v_mov_b64_e32 v[30:31], 0
	v_mov_b64_e32 v[32:33], 0
	v_mov_b64_e32 v[42:43], 0
	v_mov_b64_e32 v[44:45], 0
	v_mov_b64_e32 v[46:47], 0
	v_mov_b64_e32 v[48:49], 0
	v_mov_b64_e32 v[58:59], 0
	v_mov_b64_e32 v[60:61], 0
	v_mov_b64_e32 v[62:63], 0
	v_mov_b64_e32 v[64:65], 0
	v_mov_b64_e32 v[66:67], 0
	v_mov_b64_e32 v[68:69], 0
	v_mov_b64_e32 v[70:71], 0
	v_mov_b64_e32 v[72:73], 0
	v_mov_b64_e32 v[82:83], 0
	v_mov_b64_e32 v[84:85], 0
	v_mov_b64_e32 v[86:87], 0
	v_mov_b64_e32 v[88:89], 0
	s_waitcnt vmcnt(0)
	v_mov_b64_e32 v[98:99], 0
	v_mov_b64_e32 v[100:101], 0
	v_mov_b64_e32 v[102:103], 0
	v_mov_b64_e32 v[104:105], 0
	v_mov_b64_e32 v[114:115], 0
	v_mov_b64_e32 v[116:117], 0
	v_mov_b64_e32 v[118:119], 0
	v_mov_b64_e32 v[120:121], 0
	v_mov_b64_e32 v[74:75], 0
	v_mov_b64_e32 v[76:77], 0
	v_mov_b64_e32 v[78:79], 0
	v_mov_b64_e32 v[80:81], 0
	v_mov_b64_e32 v[90:91], 0
	v_mov_b64_e32 v[92:93], 0
	v_mov_b64_e32 v[94:95], 0
	v_mov_b64_e32 v[96:97], 0
	v_mov_b64_e32 v[106:107], 0
	v_mov_b64_e32 v[108:109], 0
	v_mov_b64_e32 v[110:111], 0
	v_mov_b64_e32 v[112:113], 0
	v_mov_b64_e32 v[122:123], 0
	v_mov_b64_e32 v[124:125], 0
	v_mov_b64_e32 v[126:127], 0
	v_mov_b64_e32 v[128:129], 0

.LBB0_543:
	s_add_u32 s76, s8, 0x100
	v_mov_b64_e32 v[2:3], 0
	s_addc_u32 s84, s9, 0
	s_mov_b32 s85, -2
	v_mov_b64_e32 v[4:5], 0
	v_mov_b64_e32 v[6:7], 0
	v_mov_b64_e32 v[8:9], 0
	v_mov_b64_e32 v[18:19], 0
	v_mov_b64_e32 v[20:21], 0
	v_mov_b64_e32 v[22:23], 0
	v_mov_b64_e32 v[24:25], 0
	v_mov_b64_e32 v[34:35], 0
	v_mov_b64_e32 v[36:37], 0
	v_mov_b64_e32 v[38:39], 0
	v_mov_b64_e32 v[40:41], 0
	v_mov_b64_e32 v[50:51], 0
	v_mov_b64_e32 v[52:53], 0
	v_mov_b64_e32 v[54:55], 0
	v_mov_b64_e32 v[56:57], 0
	v_mov_b64_e32 v[10:11], 0
	v_mov_b64_e32 v[12:13], 0
	v_mov_b64_e32 v[14:15], 0
	v_mov_b64_e32 v[16:17], 0
	v_mov_b64_e32 v[26:27], 0
	v_mov_b64_e32 v[28:29], 0
	v_mov_b64_e32 v[30:31], 0
	v_mov_b64_e32 v[32:33], 0
	v_mov_b64_e32 v[42:43], 0
	v_mov_b64_e32 v[44:45], 0
	v_mov_b64_e32 v[46:47], 0
	v_mov_b64_e32 v[48:49], 0
	v_mov_b64_e32 v[58:59], 0
	v_mov_b64_e32 v[60:61], 0
	v_mov_b64_e32 v[62:63], 0
	v_mov_b64_e32 v[64:65], 0
	v_mov_b64_e32 v[66:67], 0
	v_mov_b64_e32 v[68:69], 0
	v_mov_b64_e32 v[70:71], 0
	v_mov_b64_e32 v[72:73], 0
	v_mov_b64_e32 v[82:83], 0
	v_mov_b64_e32 v[84:85], 0
	v_mov_b64_e32 v[86:87], 0
	v_mov_b64_e32 v[88:89], 0
	s_waitcnt vmcnt(0)
	v_mov_b64_e32 v[98:99], 0
	v_mov_b64_e32 v[100:101], 0
	v_mov_b64_e32 v[102:103], 0
	v_mov_b64_e32 v[104:105], 0
	v_mov_b64_e32 v[114:115], 0
	v_mov_b64_e32 v[116:117], 0
	v_mov_b64_e32 v[118:119], 0
	v_mov_b64_e32 v[120:121], 0
	v_mov_b64_e32 v[74:75], 0
	v_mov_b64_e32 v[76:77], 0
	v_mov_b64_e32 v[78:79], 0
	v_mov_b64_e32 v[80:81], 0
	v_mov_b64_e32 v[90:91], 0
	v_mov_b64_e32 v[92:93], 0
	v_mov_b64_e32 v[94:95], 0
	v_mov_b64_e32 v[96:97], 0
	v_mov_b64_e32 v[106:107], 0
	v_mov_b64_e32 v[108:109], 0
	v_mov_b64_e32 v[110:111], 0
	v_mov_b64_e32 v[112:113], 0
	v_mov_b64_e32 v[122:123], 0
	v_mov_b64_e32 v[124:125], 0
	v_mov_b64_e32 v[126:127], 0
	v_mov_b64_e32 v[128:129], 0

.LBB0_601:
	s_ashr_i32 s17, s16, 31
	s_lshl_b64 s[12:13], s[16:17], 17
	s_add_u32 s20, s0, s12
	s_addc_u32 s21, s1, s13
	s_and_b64 s[4:5], s[4:5], exec
	v_mov_b64_e32 v[2:3], 0
	s_cselect_b32 s17, s21, s23
	s_cselect_b32 s89, s20, s22
	s_mov_b64 s[28:29], 0
	s_mov_b64 s[4:5], -1
	s_mov_b64 s[26:27], 0
	v_mov_b64_e32 v[4:5], 0
	v_mov_b64_e32 v[6:7], 0
	v_mov_b64_e32 v[8:9], 0
	v_mov_b64_e32 v[18:19], 0
	v_mov_b64_e32 v[20:21], 0
	v_mov_b64_e32 v[22:23], 0
	v_mov_b64_e32 v[24:25], 0
	v_mov_b64_e32 v[34:35], 0
	v_mov_b64_e32 v[36:37], 0
	v_mov_b64_e32 v[38:39], 0
	v_mov_b64_e32 v[40:41], 0
	v_mov_b64_e32 v[50:51], 0
	v_mov_b64_e32 v[52:53], 0
	v_mov_b64_e32 v[54:55], 0
	v_mov_b64_e32 v[56:57], 0
	v_mov_b64_e32 v[10:11], 0
	v_mov_b64_e32 v[12:13], 0
	v_mov_b64_e32 v[14:15], 0
	v_mov_b64_e32 v[16:17], 0
	v_mov_b64_e32 v[26:27], 0
	v_mov_b64_e32 v[28:29], 0
	v_mov_b64_e32 v[30:31], 0
	v_mov_b64_e32 v[32:33], 0
	v_mov_b64_e32 v[42:43], 0
	v_mov_b64_e32 v[44:45], 0
	v_mov_b64_e32 v[46:47], 0
	v_mov_b64_e32 v[48:49], 0
	v_mov_b64_e32 v[58:59], 0
	v_mov_b64_e32 v[60:61], 0
	v_mov_b64_e32 v[62:63], 0
	v_mov_b64_e32 v[64:65], 0
	v_mov_b64_e32 v[66:67], 0
	v_mov_b64_e32 v[68:69], 0
	v_mov_b64_e32 v[70:71], 0
	v_mov_b64_e32 v[72:73], 0
	v_mov_b64_e32 v[82:83], 0
	v_mov_b64_e32 v[84:85], 0
	v_mov_b64_e32 v[86:87], 0
	v_mov_b64_e32 v[88:89], 0
	s_waitcnt vmcnt(0)
	v_mov_b64_e32 v[98:99], 0
	v_mov_b64_e32 v[100:101], 0
	v_mov_b64_e32 v[102:103], 0
	v_mov_b64_e32 v[104:105], 0
	v_mov_b64_e32 v[114:115], 0
	v_mov_b64_e32 v[116:117], 0
	v_mov_b64_e32 v[118:119], 0
	v_mov_b64_e32 v[120:121], 0
	v_mov_b64_e32 v[74:75], 0
	v_mov_b64_e32 v[76:77], 0
	v_mov_b64_e32 v[78:79], 0
	v_mov_b64_e32 v[80:81], 0
	v_mov_b64_e32 v[90:91], 0
	v_mov_b64_e32 v[92:93], 0
	v_mov_b64_e32 v[94:95], 0
	v_mov_b64_e32 v[96:97], 0
	v_mov_b64_e32 v[106:107], 0
	v_mov_b64_e32 v[108:109], 0
	v_mov_b64_e32 v[110:111], 0
	v_mov_b64_e32 v[112:113], 0
	v_mov_b64_e32 v[122:123], 0
	v_mov_b64_e32 v[124:125], 0
	v_mov_b64_e32 v[126:127], 0
	v_mov_b64_e32 v[128:129], 0

.LBB0_691:
	s_ashr_i32 s27, s26, 31
	s_lshl_b64 s[12:13], s[26:27], 19
	s_add_u32 s28, s16, s12
	s_addc_u32 s29, s17, s13
	s_and_b64 s[12:13], s[8:9], exec
	s_cselect_b32 s11, s29, s47
	s_cselect_b32 s27, s28, s46
	s_ashr_i32 s25, s24, 31
	s_lshl_b64 s[12:13], s[24:25], 19
	s_add_u32 s30, s0, s12
	s_addc_u32 s31, s1, s13
	s_and_b64 s[12:13], s[8:9], exec
	s_cselect_b32 s25, s31, s43
	s_cselect_b32 s35, s30, s42
	s_add_u32 s85, s42, 0x100
	s_addc_u32 s86, s43, 0
	s_add_u32 s42, s46, 0x40080
	v_mov_b64_e32 v[2:3], 0
	s_addc_u32 s43, s47, 0
	s_mov_b32 s90, -2
	v_mov_b64_e32 v[4:5], 0
	v_mov_b64_e32 v[6:7], 0
	v_mov_b64_e32 v[8:9], 0
	v_mov_b64_e32 v[18:19], 0
	v_mov_b64_e32 v[20:21], 0
	v_mov_b64_e32 v[22:23], 0
	v_mov_b64_e32 v[24:25], 0
	v_mov_b64_e32 v[34:35], 0
	v_mov_b64_e32 v[36:37], 0
	v_mov_b64_e32 v[38:39], 0
	v_mov_b64_e32 v[40:41], 0
	v_mov_b64_e32 v[62:63], 0
	v_mov_b64_e32 v[64:65], 0
	v_mov_b64_e32 v[66:67], 0
	v_mov_b64_e32 v[68:69], 0
	v_mov_b64_e32 v[10:11], 0
	v_mov_b64_e32 v[12:13], 0
	v_mov_b64_e32 v[14:15], 0
	v_mov_b64_e32 v[16:17], 0
	v_mov_b64_e32 v[26:27], 0
	v_mov_b64_e32 v[28:29], 0
	v_mov_b64_e32 v[30:31], 0
	v_mov_b64_e32 v[32:33], 0
	v_mov_b64_e32 v[46:47], 0
	v_mov_b64_e32 v[48:49], 0
	v_mov_b64_e32 v[50:51], 0
	v_mov_b64_e32 v[52:53], 0
	v_mov_b64_e32 v[74:75], 0
	v_mov_b64_e32 v[76:77], 0
	v_mov_b64_e32 v[78:79], 0
	v_mov_b64_e32 v[80:81], 0
	v_mov_b64_e32 v[82:83], 0
	v_mov_b64_e32 v[84:85], 0
	v_mov_b64_e32 v[86:87], 0
	v_mov_b64_e32 v[88:89], 0
	s_waitcnt vmcnt(0)
	v_mov_b64_e32 v[98:99], 0
	v_mov_b64_e32 v[100:101], 0
	v_mov_b64_e32 v[102:103], 0
	v_mov_b64_e32 v[104:105], 0
	v_mov_b64_e32 v[114:115], 0
	v_mov_b64_e32 v[116:117], 0
	v_mov_b64_e32 v[118:119], 0
	v_mov_b64_e32 v[120:121], 0
	v_mov_b64_e32 v[130:131], 0
	v_mov_b64_e32 v[132:133], 0
	v_mov_b64_e32 v[134:135], 0
	v_mov_b64_e32 v[136:137], 0
	v_mov_b64_e32 v[90:91], 0
	v_mov_b64_e32 v[92:93], 0
	v_mov_b64_e32 v[94:95], 0
	v_mov_b64_e32 v[96:97], 0
	v_mov_b64_e32 v[106:107], 0
	v_mov_b64_e32 v[108:109], 0
	v_mov_b64_e32 v[110:111], 0
	v_mov_b64_e32 v[112:113], 0
	v_mov_b64_e32 v[122:123], 0
	v_mov_b64_e32 v[124:125], 0
	v_mov_b64_e32 v[126:127], 0
	v_mov_b64_e32 v[128:129], 0
	v_mov_b64_e32 v[138:139], 0
	v_mov_b64_e32 v[140:141], 0
	v_mov_b64_e32 v[142:143], 0
	v_mov_b64_e32 v[144:145], 0

.LBB0_878:
	s_ashr_i32 s17, s16, 31
	s_lshl_b64 s[12:13], s[16:17], 19
	s_add_u32 s18, s0, s12
	s_addc_u32 s19, s1, s13
	s_and_b64 s[12:13], s[4:5], exec
	s_cselect_b32 s14, s19, s29
	s_cselect_b32 s17, s18, s28
	s_ashr_i32 s11, s10, 31
	s_lshl_b64 s[12:13], s[10:11], 19
	s_add_u32 s20, s96, s12
	s_addc_u32 s21, s97, s13
	s_and_b64 s[12:13], s[4:5], exec
	s_cselect_b32 s11, s21, s27
	s_cselect_b32 s23, s20, s26
	s_add_u32 s33, s26, 0x100
	s_addc_u32 s76, s27, 0
	s_add_u32 s26, s28, 0x40080
	s_waitcnt lgkmcnt(0)
	v_mov_b64_e32 v[2:3], 0
	s_addc_u32 s27, s29, 0
	s_mov_b32 s84, -2
	v_mov_b64_e32 v[4:5], 0
	v_mov_b64_e32 v[6:7], 0
	v_mov_b64_e32 v[8:9], 0
	v_mov_b64_e32 v[18:19], 0
	v_mov_b64_e32 v[20:21], 0
	v_mov_b64_e32 v[22:23], 0
	v_mov_b64_e32 v[24:25], 0
	v_mov_b64_e32 v[34:35], 0
	v_mov_b64_e32 v[36:37], 0
	v_mov_b64_e32 v[38:39], 0
	v_mov_b64_e32 v[40:41], 0
	v_mov_b64_e32 v[50:51], 0
	v_mov_b64_e32 v[52:53], 0
	v_mov_b64_e32 v[54:55], 0
	v_mov_b64_e32 v[56:57], 0
	v_mov_b64_e32 v[10:11], 0
	v_mov_b64_e32 v[12:13], 0
	v_mov_b64_e32 v[14:15], 0
	v_mov_b64_e32 v[16:17], 0
	v_mov_b64_e32 v[26:27], 0
	v_mov_b64_e32 v[28:29], 0
	v_mov_b64_e32 v[30:31], 0
	v_mov_b64_e32 v[32:33], 0
	v_mov_b64_e32 v[42:43], 0
	v_mov_b64_e32 v[44:45], 0
	v_mov_b64_e32 v[46:47], 0
	v_mov_b64_e32 v[48:49], 0
	v_mov_b64_e32 v[58:59], 0
	v_mov_b64_e32 v[60:61], 0
	v_mov_b64_e32 v[62:63], 0
	v_mov_b64_e32 v[64:65], 0
	v_mov_b64_e32 v[66:67], 0
	v_mov_b64_e32 v[68:69], 0
	v_mov_b64_e32 v[70:71], 0
	v_mov_b64_e32 v[72:73], 0
	v_mov_b64_e32 v[82:83], 0
	v_mov_b64_e32 v[84:85], 0
	v_mov_b64_e32 v[86:87], 0
	v_mov_b64_e32 v[88:89], 0
	s_waitcnt vmcnt(0)
	v_mov_b64_e32 v[98:99], 0
	v_mov_b64_e32 v[100:101], 0
	v_mov_b64_e32 v[102:103], 0
	v_mov_b64_e32 v[104:105], 0
	v_mov_b64_e32 v[114:115], 0
	v_mov_b64_e32 v[116:117], 0
	v_mov_b64_e32 v[118:119], 0
	v_mov_b64_e32 v[120:121], 0
	v_mov_b64_e32 v[74:75], 0
	v_mov_b64_e32 v[76:77], 0
	v_mov_b64_e32 v[78:79], 0
	v_mov_b64_e32 v[80:81], 0
	v_mov_b64_e32 v[90:91], 0
	v_mov_b64_e32 v[92:93], 0
	v_mov_b64_e32 v[94:95], 0
	v_mov_b64_e32 v[96:97], 0
	v_mov_b64_e32 v[106:107], 0
	v_mov_b64_e32 v[108:109], 0
	v_mov_b64_e32 v[110:111], 0
	v_mov_b64_e32 v[112:113], 0
	v_mov_b64_e32 v[122:123], 0
	v_mov_b64_e32 v[124:125], 0
	v_mov_b64_e32 v[126:127], 0
	v_mov_b64_e32 v[128:129], 0

.LBB0_954:
	s_ashr_i32 s17, s16, 31
	s_lshl_b64 s[12:13], s[16:17], 19
	s_add_u32 s18, s4, s12
	s_addc_u32 s19, s5, s13
	s_and_b64 s[12:13], s[2:3], exec
	s_cselect_b32 s17, s19, s27
	s_cselect_b32 s23, s18, s26
	s_ashr_i32 s11, s10, 31
	s_lshl_b64 s[12:13], s[10:11], 19
	s_add_u32 s20, s0, s12
	s_addc_u32 s21, s1, s13
	s_and_b64 s[12:13], s[2:3], exec
	s_cselect_b32 s11, s21, s25
	s_cselect_b32 s33, s20, s24
	s_add_u32 s76, s24, 0x100
	s_addc_u32 s84, s25, 0
	s_add_u32 s24, s26, 0x40080
	v_mov_b64_e32 v[2:3], 0
	s_addc_u32 s25, s27, 0
	s_mov_b32 s85, -2
	v_mov_b64_e32 v[4:5], 0
	v_mov_b64_e32 v[6:7], 0
	v_mov_b64_e32 v[8:9], 0
	v_mov_b64_e32 v[18:19], 0
	v_mov_b64_e32 v[20:21], 0
	v_mov_b64_e32 v[22:23], 0
	v_mov_b64_e32 v[24:25], 0
	v_mov_b64_e32 v[34:35], 0
	v_mov_b64_e32 v[36:37], 0
	v_mov_b64_e32 v[38:39], 0
	v_mov_b64_e32 v[40:41], 0
	v_mov_b64_e32 v[50:51], 0
	v_mov_b64_e32 v[52:53], 0
	v_mov_b64_e32 v[54:55], 0
	v_mov_b64_e32 v[56:57], 0
	v_mov_b64_e32 v[10:11], 0
	v_mov_b64_e32 v[12:13], 0
	v_mov_b64_e32 v[14:15], 0
	v_mov_b64_e32 v[16:17], 0
	v_mov_b64_e32 v[26:27], 0
	v_mov_b64_e32 v[28:29], 0
	v_mov_b64_e32 v[30:31], 0
	v_mov_b64_e32 v[32:33], 0
	v_mov_b64_e32 v[42:43], 0
	v_mov_b64_e32 v[44:45], 0
	v_mov_b64_e32 v[46:47], 0
	v_mov_b64_e32 v[48:49], 0
	v_mov_b64_e32 v[58:59], 0
	v_mov_b64_e32 v[60:61], 0
	v_mov_b64_e32 v[62:63], 0
	v_mov_b64_e32 v[64:65], 0
	v_mov_b64_e32 v[66:67], 0
	v_mov_b64_e32 v[68:69], 0
	v_mov_b64_e32 v[70:71], 0
	v_mov_b64_e32 v[72:73], 0
	v_mov_b64_e32 v[82:83], 0
	v_mov_b64_e32 v[84:85], 0
	v_mov_b64_e32 v[86:87], 0
	v_mov_b64_e32 v[88:89], 0
	s_waitcnt vmcnt(0)
	v_mov_b64_e32 v[98:99], 0
	v_mov_b64_e32 v[100:101], 0
	v_mov_b64_e32 v[102:103], 0
	v_mov_b64_e32 v[104:105], 0
	v_mov_b64_e32 v[114:115], 0
	v_mov_b64_e32 v[116:117], 0
	v_mov_b64_e32 v[118:119], 0
	v_mov_b64_e32 v[120:121], 0
	v_mov_b64_e32 v[74:75], 0
	v_mov_b64_e32 v[76:77], 0
	v_mov_b64_e32 v[78:79], 0
	v_mov_b64_e32 v[80:81], 0
	v_mov_b64_e32 v[90:91], 0
	v_mov_b64_e32 v[92:93], 0
	v_mov_b64_e32 v[94:95], 0
	v_mov_b64_e32 v[96:97], 0
	v_mov_b64_e32 v[106:107], 0
	v_mov_b64_e32 v[108:109], 0
	v_mov_b64_e32 v[110:111], 0
	v_mov_b64_e32 v[112:113], 0
	v_mov_b64_e32 v[122:123], 0
	v_mov_b64_e32 v[124:125], 0
	v_mov_b64_e32 v[126:127], 0
	v_mov_b64_e32 v[128:129], 0

.LBB0_1028:
	s_add_u32 s76, s24, 0x100
	s_waitcnt lgkmcnt(0)
	v_mov_b64_e32 v[2:3], 0
	s_addc_u32 s80, s25, 0
	s_mov_b32 s81, -2
	v_mov_b64_e32 v[4:5], 0
	v_mov_b64_e32 v[6:7], 0
	v_mov_b64_e32 v[8:9], 0
	v_mov_b64_e32 v[18:19], 0
	v_mov_b64_e32 v[20:21], 0
	v_mov_b64_e32 v[22:23], 0
	v_mov_b64_e32 v[24:25], 0
	v_mov_b64_e32 v[34:35], 0
	v_mov_b64_e32 v[36:37], 0
	v_mov_b64_e32 v[38:39], 0
	v_mov_b64_e32 v[40:41], 0
	v_mov_b64_e32 v[50:51], 0
	v_mov_b64_e32 v[52:53], 0
	v_mov_b64_e32 v[54:55], 0
	v_mov_b64_e32 v[56:57], 0
	v_mov_b64_e32 v[10:11], 0
	v_mov_b64_e32 v[12:13], 0
	v_mov_b64_e32 v[14:15], 0
	v_mov_b64_e32 v[16:17], 0
	v_mov_b64_e32 v[26:27], 0
	v_mov_b64_e32 v[28:29], 0
	v_mov_b64_e32 v[30:31], 0
	v_mov_b64_e32 v[32:33], 0
	v_mov_b64_e32 v[42:43], 0
	v_mov_b64_e32 v[44:45], 0
	v_mov_b64_e32 v[46:47], 0
	v_mov_b64_e32 v[48:49], 0
	v_mov_b64_e32 v[58:59], 0
	v_mov_b64_e32 v[60:61], 0
	v_mov_b64_e32 v[62:63], 0
	v_mov_b64_e32 v[64:65], 0
	v_mov_b64_e32 v[66:67], 0
	v_mov_b64_e32 v[68:69], 0
	v_mov_b64_e32 v[70:71], 0
	v_mov_b64_e32 v[72:73], 0
	v_mov_b64_e32 v[82:83], 0
	v_mov_b64_e32 v[84:85], 0
	v_mov_b64_e32 v[86:87], 0
	v_mov_b64_e32 v[88:89], 0
	s_waitcnt vmcnt(0)
	v_mov_b64_e32 v[98:99], 0
	v_mov_b64_e32 v[100:101], 0
	v_mov_b64_e32 v[102:103], 0
	v_mov_b64_e32 v[104:105], 0
	v_mov_b64_e32 v[114:115], 0
	v_mov_b64_e32 v[116:117], 0
	v_mov_b64_e32 v[118:119], 0
	v_mov_b64_e32 v[120:121], 0
	v_mov_b64_e32 v[74:75], 0
	v_mov_b64_e32 v[76:77], 0
	v_mov_b64_e32 v[78:79], 0
	v_mov_b64_e32 v[80:81], 0
	v_mov_b64_e32 v[90:91], 0
	v_mov_b64_e32 v[92:93], 0
	v_mov_b64_e32 v[94:95], 0
	v_mov_b64_e32 v[96:97], 0
	v_mov_b64_e32 v[106:107], 0
	v_mov_b64_e32 v[108:109], 0
	v_mov_b64_e32 v[110:111], 0
	v_mov_b64_e32 v[112:113], 0
	v_mov_b64_e32 v[122:123], 0
	v_mov_b64_e32 v[124:125], 0
	v_mov_b64_e32 v[126:127], 0
	v_mov_b64_e32 v[128:129], 0
